# v8b: v8 + hazard fix (2 wait states before permlane32_swap)
# speedup vs baseline: 1.0025x; 1.0001x over previous
.LBB0_526:
	ds_read_b128 v[64:67], v192 offset:49152
	ds_read_b128 v[68:71], v192 offset:57344
	ds_read_b128 v[232:235], v200 offset:49152
	ds_read_b128 v[236:239], v200 offset:57344
	ds_read_b128 v[250:253], v199 offset:49152
	ds_read_b128 v[244:247], v199 offset:57344
	ds_read_b128 v[212:215], v198 offset:49152
	ds_read_b128 v[216:219], v198 offset:57344
	v_add_f32_e32 v162, 0, v163
	v_add_f32_e32 v162, v177, v162
	s_waitcnt lgkmcnt(6)
	v_mfma_f32_32x32x16_bf16 v[80:95], v[64:67], v[118:121], 0
	v_add_f32_e32 v162, v164, v162
	v_add_f32_e32 v162, v207, v162
	v_add_f32_e32 v162, v176, v162
	v_add_f32_e32 v162, v210, v162
	v_mfma_f32_32x32x16_bf16 v[64:79], v[68:71], v[118:121], 0
	v_add_f32_e32 v162, v165, v162
	v_add_f32_e32 v162, v175, v162
	v_add_f32_e32 v162, v166, v162
	v_add_f32_e32 v162, v173, v162
	v_add_f32_e32 v162, v167, v162
	s_waitcnt lgkmcnt(4)
	v_mfma_f32_32x32x16_bf16 v[80:95], v[232:235], v[114:117], v[80:95]
	ds_read_b128 v[232:235], v195 offset:49152
	v_add_f32_e32 v162, v174, v162
	v_exp_f32_e32 v160, v160
	v_add_f32_e32 v162, v168, v162
	v_exp_f32_e32 v161, v161
	v_mfma_f32_32x32x16_bf16 v[64:79], v[236:239], v[114:117], v[64:79]
	ds_read_b128 v[236:239], v195 offset:57344
	v_add_f32_e32 v162, v171, v162
	v_exp_f32_e32 v158, v158
	v_add_f32_e32 v162, v169, v162
	v_exp_f32_e32 v159, v159
	s_waitcnt lgkmcnt(4)
	v_mfma_f32_32x32x16_bf16 v[80:95], v[250:253], v[126:129], v[80:95]
	ds_read_b128 v[250:253], v193 offset:49152
	v_add_f32_e32 v162, v172, v162
	v_exp_f32_e32 v154, v154
	v_add_f32_e32 v162, v160, v162
	v_exp_f32_e32 v155, v155
	v_mfma_f32_32x32x16_bf16 v[64:79], v[244:247], v[126:129], v[64:79]
	ds_read_b128 v[244:247], v193 offset:57344
	v_add_f32_e32 v162, v161, v162
	v_exp_f32_e32 v150, v150
	v_add_f32_e32 v162, v158, v162
	v_exp_f32_e32 v151, v151
	s_waitcnt lgkmcnt(4)
	v_mfma_f32_32x32x16_bf16 v[80:95], v[212:215], v[122:125], v[80:95]
	ds_read_b128 v[212:215], v202 offset:49152
	v_add_f32_e32 v162, v159, v162
	v_exp_f32_e32 v148, v148
	v_add_f32_e32 v162, v154, v162
	v_exp_f32_e32 v149, v149
	v_mfma_f32_32x32x16_bf16 v[64:79], v[216:219], v[122:125], v[64:79]
	ds_read_b128 v[216:219], v202 offset:57344
	v_add_f32_e32 v162, v155, v162
	v_exp_f32_e32 v156, v156
	v_add_f32_e32 v162, v150, v162
	v_exp_f32_e32 v157, v157
	s_waitcnt lgkmcnt(4)
	v_mfma_f32_32x32x16_bf16 v[80:95], v[232:235], v[110:113], v[80:95]
	ds_read_b128 v[232:235], v201 offset:49152
	v_add_f32_e32 v162, v151, v162
	v_exp_f32_e32 v152, v152
	v_add_f32_e32 v162, v148, v162
	v_exp_f32_e32 v153, v153
	v_mfma_f32_32x32x16_bf16 v[64:79], v[236:239], v[110:113], v[64:79]
	ds_read_b128 v[236:239], v201 offset:57344
	v_add_f32_e32 v162, v149, v162
	v_exp_f32_e32 v146, v146
	v_add_f32_e32 v162, v156, v162
	v_exp_f32_e32 v147, v147
	s_waitcnt lgkmcnt(4)
	v_mfma_f32_32x32x16_bf16 v[80:95], v[250:253], v[106:109], v[80:95]
	v_add_f32_e32 v162, v157, v162
	v_add_f32_e32 v162, v152, v162
	v_add_f32_e32 v162, v153, v162
	v_add_f32_e32 v162, v146, v162
	v_add_f32_e32 v204, v147, v162
	v_mov_b32_e32 v205, v204
	v_mfma_f32_32x32x16_bf16 v[64:79], v[244:247], v[106:109], v[64:79]
	s_nop 0
	v_permlane32_swap_b32_e32 v204, v205
	v_cvt_pk_bf16_f32 v162, v163, v177
	v_cvt_pk_bf16_f32 v163, v164, v207
	v_cvt_pk_bf16_f32 v164, v176, v210
	s_waitcnt lgkmcnt(2)
	v_mfma_f32_32x32x16_bf16 v[80:95], v[212:215], v[102:105], v[80:95]
	v_cvt_pk_bf16_f32 v165, v165, v175
	v_cvt_pk_bf16_f32 v166, v166, v173
	v_cvt_pk_bf16_f32 v167, v167, v174
	v_cvt_pk_bf16_f32 v168, v168, v171
	v_mfma_f32_32x32x16_bf16 v[64:79], v[216:219], v[102:105], v[64:79]
	v_cvt_pk_bf16_f32 v169, v169, v172
	v_cvt_pk_bf16_f32 v172, v160, v161
	v_cvt_pk_bf16_f32 v173, v158, v159
	v_cvt_pk_bf16_f32 v174, v154, v155
	ds_read_b64_tr_b16 v[210:211], v187 offset:0x0
	ds_read_b64_tr_b16 v[212:213], v187 offset:0x800
	ds_read_b64_tr_b16 v[214:215], v187 offset:0x200
	ds_read_b64_tr_b16 v[216:217], v187 offset:0xa00
	ds_read_b64_tr_b16 v[218:219], v187 offset:0x400
	ds_read_b64_tr_b16 v[220:221], v187 offset:0xc00
	ds_read_b64_tr_b16 v[222:223], v187 offset:0x600
	ds_read_b64_tr_b16 v[224:225], v187 offset:0xe00
	s_waitcnt lgkmcnt(8)
	v_mfma_f32_32x32x16_bf16 v[80:95], v[232:235], v[98:101], v[80:95]
	v_cvt_pk_bf16_f32 v175, v150, v151
	v_cvt_pk_bf16_f32 v206, v148, v149
	v_cvt_pk_bf16_f32 v207, v156, v157
	v_mfma_f32_32x32x16_bf16 v[64:79], v[236:239], v[98:101], v[64:79]
	v_cvt_pk_bf16_f32 v208, v152, v153
	v_cvt_pk_bf16_f32 v209, v146, v147
	s_nop 1
	v_permlane32_swap_b32_e32 v162, v164
	v_permlane32_swap_b32_e32 v206, v208
	v_permlane32_swap_b32_e32 v163, v165
	v_permlane32_swap_b32_e32 v166, v168
	v_permlane32_swap_b32_e32 v167, v169
	v_permlane32_swap_b32_e32 v172, v174
	v_permlane32_swap_b32_e32 v173, v175
	v_permlane32_swap_b32_e32 v207, v209
	s_waitcnt vmcnt(0)
	ds_write_b128 v188, v[134:137] offset:32768
	ds_write_b128 v189, v[142:145] offset:32768
	global_load_dwordx4 v[146:149], v178, s[66:67]
	global_load_dwordx4 v[150:153], v179, s[66:67]
	global_load_dwordx4 v[154:157], v178, s[98:99]
	global_load_dwordx4 v[158:161], v179, s[98:99]
	s_add_u32 s66, s66, 0x4000
	s_addc_u32 s67, s67, 0
	s_add_u32 s98, s98, 0x4000
	s_addc_u32 s99, s99, 0
	s_waitcnt lgkmcnt(6)
	v_mfma_f32_32x32x16_bf16 v[0:15], v[162:165], v[210:213], v[0:15]
	ds_read_b64_tr_b16 v[210:211], v187 offset:0x1000
	ds_read_b64_tr_b16 v[212:213], v187 offset:0x1800
	v_max_f32_e32 v240, v80, v81
	v_max3_f32 v240, v240, v82, v83
	v_max3_f32 v240, v240, v84, v85
	v_max3_f32 v240, v240, v86, v87
	v_max3_f32 v240, v240, v88, v89
	v_mfma_f32_32x32x16_bf16 v[48:63], v[162:165], v[214:217], v[48:63]
	ds_read_b64_tr_b16 v[214:215], v187 offset:0x1200
	ds_read_b64_tr_b16 v[216:217], v187 offset:0x1a00
	v_max3_f32 v240, v240, v90, v91
	v_max3_f32 v240, v240, v92, v93
	v_max3_f32 v240, v240, v94, v95
	v_max3_f32 v240, v240, v64, v65
	v_max3_f32 v240, v240, v66, v67
	v_max3_f32 v240, v240, v68, v69
	s_waitcnt lgkmcnt(6)
	v_mfma_f32_32x32x16_bf16 v[32:47], v[162:165], v[218:221], v[32:47]
	ds_read_b64_tr_b16 v[218:219], v187 offset:0x1400
	ds_read_b64_tr_b16 v[220:221], v187 offset:0x1c00
	v_max3_f32 v240, v240, v70, v71
	v_max3_f32 v240, v240, v72, v73
	v_max3_f32 v240, v240, v74, v75
	v_max3_f32 v240, v240, v76, v77
	v_max3_f32 v240, v240, v78, v79
	v_mfma_f32_32x32x16_bf16 v[16:31], v[162:165], v[222:225], v[16:31]
	ds_read_b64_tr_b16 v[222:223], v187 offset:0x1600
	ds_read_b64_tr_b16 v[224:225], v187 offset:0x1e00
	v_mov_b32_e32 v241, v240
	s_nop 1
	v_permlane32_swap_b32_e32 v240, v241
	v_max_f32_e32 v240, v240, v241
	v_sub_f32_e32 v241, v240, v170
	v_cmp_ge_f32_e32 vcc, s92, v241
	s_waitcnt lgkmcnt(4)
	v_mfma_f32_32x32x16_bf16 v[0:15], v[166:169], v[210:213], v[0:15]
	ds_read_b64_tr_b16 v[210:211], v187 offset:0x2000
	ds_read_b64_tr_b16 v[212:213], v187 offset:0x2800
	v_max_f32_e32 v240, v170, v240
	v_sub_f32_e32 v241, v170, v240
	v_mul_f32_e32 v241, 0x3e0293ee, v241
	v_exp_f32_e32 v241, v241
	s_cmp_eq_u64 vcc, exec
	s_cselect_b64 s[42:43], -1, 0
	v_mfma_f32_32x32x16_bf16 v[48:63], v[166:169], v[214:217], v[48:63]
	ds_read_b64_tr_b16 v[214:215], v187 offset:0x2200
	ds_read_b64_tr_b16 v[216:217], v187 offset:0x2a00
	v_cndmask_b32_e64 v242, v240, v170, s[42:43]
	v_mul_f32_e32 v243, 0xbe0293ee, v242
	v_fmamk_f32 v80, v80, 0x3e0293ee, v243
	v_fmamk_f32 v81, v81, 0x3e0293ee, v243
	v_fmamk_f32 v82, v82, 0x3e0293ee, v243
	v_fmamk_f32 v83, v83, 0x3e0293ee, v243
	s_waitcnt lgkmcnt(4)
	v_mfma_f32_32x32x16_bf16 v[32:47], v[166:169], v[218:221], v[32:47]
	ds_read_b64_tr_b16 v[218:219], v187 offset:0x2400
	ds_read_b64_tr_b16 v[220:221], v187 offset:0x2c00
	v_fmamk_f32 v84, v84, 0x3e0293ee, v243
	v_fmamk_f32 v85, v85, 0x3e0293ee, v243
	v_fmamk_f32 v86, v86, 0x3e0293ee, v243
	v_fmamk_f32 v87, v87, 0x3e0293ee, v243
	v_fmamk_f32 v88, v88, 0x3e0293ee, v243
	v_fmamk_f32 v89, v89, 0x3e0293ee, v243
	v_mfma_f32_32x32x16_bf16 v[16:31], v[166:169], v[222:225], v[16:31]
	ds_read_b64_tr_b16 v[222:223], v187 offset:0x2600
	ds_read_b64_tr_b16 v[224:225], v187 offset:0x2e00
	v_fmamk_f32 v90, v90, 0x3e0293ee, v243
	v_fmamk_f32 v91, v91, 0x3e0293ee, v243
	v_fmamk_f32 v92, v92, 0x3e0293ee, v243
	v_fmamk_f32 v93, v93, 0x3e0293ee, v243
	v_fmamk_f32 v94, v94, 0x3e0293ee, v243
	v_fmamk_f32 v95, v95, 0x3e0293ee, v243
	s_waitcnt lgkmcnt(4)
	v_mfma_f32_32x32x16_bf16 v[0:15], v[172:175], v[210:213], v[0:15]
	ds_read_b64_tr_b16 v[210:211], v187 offset:0x3000
	ds_read_b64_tr_b16 v[212:213], v187 offset:0x3800
	v_exp_f32_e32 v177, v81
	v_exp_f32_e32 v176, v83
	v_exp_f32_e32 v171, v93
	v_mfma_f32_32x32x16_bf16 v[48:63], v[172:175], v[214:217], v[48:63]
	ds_read_b64_tr_b16 v[214:215], v187 offset:0x3200
	ds_read_b64_tr_b16 v[216:217], v187 offset:0x3a00
	v_exp_f32_e32 v170, v95
	v_exp_f32_e32 v162, v80
	v_exp_f32_e32 v163, v82
	s_waitcnt lgkmcnt(4)
	v_mfma_f32_32x32x16_bf16 v[32:47], v[172:175], v[218:221], v[32:47]
	ds_read_b64_tr_b16 v[218:219], v187 offset:0x3400
	ds_read_b64_tr_b16 v[220:221], v187 offset:0x3c00
	v_exp_f32_e32 v164, v84
	v_exp_f32_e32 v165, v86
	v_exp_f32_e32 v166, v88
	v_mfma_f32_32x32x16_bf16 v[16:31], v[172:175], v[222:225], v[16:31]
	ds_read_b64_tr_b16 v[222:223], v187 offset:0x3600
	ds_read_b64_tr_b16 v[224:225], v187 offset:0x3e00
	v_exp_f32_e32 v167, v90
	v_exp_f32_e32 v168, v92
	v_exp_f32_e32 v169, v94
	s_waitcnt lgkmcnt(4)
	v_mfma_f32_32x32x16_bf16 v[0:15], v[206:209], v[210:213], v[0:15]
	v_exp_f32_e32 v175, v85
	v_exp_f32_e32 v174, v87
	v_exp_f32_e32 v173, v89
	v_mfma_f32_32x32x16_bf16 v[48:63], v[206:209], v[214:217], v[48:63]
	v_exp_f32_e32 v172, v91
	s_waitcnt lgkmcnt(0)
	v_mfma_f32_32x32x16_bf16 v[32:47], v[206:209], v[218:221], v[32:47]
	v_mfma_f32_32x32x16_bf16 v[16:31], v[206:209], v[222:225], v[16:31]
	s_barrier
	v_cndmask_b32_e64 v206, v241, 1.0, s[42:43]
	v_cmp_gt_f32_e32 vcc, 1.0, v206
	ds_write_b128 v190, v[130:133]
	ds_write_b128 v191, v[138:141]
	s_cbranch_vccz .LBB0_530
	s_and_saveexec_b64 s[6:7], s[40:41]
	ds_write_b32 v184, v206 offset:128
	s_or_b64 exec, exec, s[6:7]
	s_waitcnt lgkmcnt(0)
	ds_read_b128 v[210:213], v182 offset:224
	ds_read_b128 v[214:217], v182 offset:192
	ds_read_b128 v[218:221], v182 offset:160
	ds_read_b128 v[222:225], v182 offset:128
	s_waitcnt lgkmcnt(3)
	v_pk_mul_f32 v[14:15], v[14:15], v[212:213]
	s_waitcnt lgkmcnt(2)
	v_pk_mul_f32 v[10:11], v[10:11], v[216:217]
	s_waitcnt lgkmcnt(1)
	v_pk_mul_f32 v[6:7], v[6:7], v[220:221]
	s_waitcnt lgkmcnt(0)
	v_pk_mul_f32 v[2:3], v[2:3], v[224:225]
	v_pk_mul_f32 v[12:13], v[12:13], v[210:211]
	v_pk_mul_f32 v[8:9], v[8:9], v[214:215]
	v_pk_mul_f32 v[4:5], v[4:5], v[218:219]
	v_pk_mul_f32 v[0:1], v[0:1], v[222:223]
	v_pk_mul_f32 v[62:63], v[62:63], v[212:213]
	v_pk_mul_f32 v[58:59], v[58:59], v[216:217]
	v_pk_mul_f32 v[54:55], v[54:55], v[220:221]
	v_pk_mul_f32 v[50:51], v[50:51], v[224:225]
	v_pk_mul_f32 v[60:61], v[60:61], v[210:211]
	v_pk_mul_f32 v[56:57], v[56:57], v[214:215]
	v_pk_mul_f32 v[52:53], v[52:53], v[218:219]
	v_pk_mul_f32 v[48:49], v[48:49], v[222:223]
	v_pk_mul_f32 v[46:47], v[46:47], v[212:213]
	v_pk_mul_f32 v[42:43], v[42:43], v[216:217]
	v_pk_mul_f32 v[38:39], v[38:39], v[220:221]
	v_pk_mul_f32 v[34:35], v[34:35], v[224:225]
	v_pk_mul_f32 v[44:45], v[44:45], v[210:211]
	v_pk_mul_f32 v[40:41], v[40:41], v[214:215]
	v_pk_mul_f32 v[36:37], v[36:37], v[218:219]
	v_pk_mul_f32 v[32:33], v[32:33], v[222:223]
	v_pk_mul_f32 v[30:31], v[30:31], v[212:213]
	v_pk_mul_f32 v[26:27], v[26:27], v[216:217]
	v_pk_mul_f32 v[22:23], v[22:23], v[220:221]
	v_pk_mul_f32 v[18:19], v[18:19], v[224:225]
	v_pk_mul_f32 v[28:29], v[28:29], v[210:211]
	v_pk_mul_f32 v[24:25], v[24:25], v[214:215]
	v_pk_mul_f32 v[20:21], v[20:21], v[218:219]
	v_pk_mul_f32 v[16:17], v[16:17], v[222:223]
